# P3 kv-up epilogue: rope-table and k_norm_g[0:64] loads issued together with the k-pe loads (one exposed latency instead of three)
# speedup vs baseline: 1.0349x; 1.0032x over previous
; DI unsigned pk_bf16(float lo, float hi) { f32x2v v = {lo, hi}; bf16x2v b = __builtin_convertvector(v, bf16x2v); return __builtin_bit_cast(unsigned, b); }
; DI bf16_t f2bf(float f) { return (bf16_t)(pk_bf16(f, 0.f) & 0xffffu); }
; DI int crow(int i, int hh) { return (i & 3) + 8 * (i >> 2) + 4 * hh; }
; DI void lds_sync() { wait_lgkm0(); bar_(); }
; DI void phase3(const Params& p, char* smem) {
;     ...
;       for (int tm = 0; tm < 4; ++tm)
; #pragma unroll
;         for (int i = 0; i < 16; ++i) { const float v = acc[tm][0][i] * ra; acc[tm][0][i] = v; if (tm < 2) ss += v * v; }
; #pragma unroll
;       for (int i = 0; i < 16; ++i) ss += kp[i] * kp[i];
;       ss += __shfl_xor(ss, 32);
;       const float rk = rsqrtf(ss * (1.f / QKD) + EPS);
; #pragma unroll
;       for (int i = 0; i < 16; ++i) kp[i] *= rk * p.k_norm_g[64 + crow(i, hh)];
;       if (lat) {
;         const int pos = key;
;         const float* tr = p.ropeTab + ((pos >> 6) * 8 + 4 * hh) * 2;
;         const float* tc = p.ropeTab + ((pos & 63) * 8 + 4 * hh) * 2;
; #pragma unroll
;         for (int i = 0; i < 4; ++i) { rope_pair(kp[i], kp[i + 4], tr + 2 * i); rope_pair(kp[8 + i], kp[12 + i], tc + 2 * i); }
;       }
;       {
;         char* kt_ = smem; char* vt_ = smem + 256 * 208;
;         char* kd = kt_ + tl * 208;
; #pragma unroll
;         for (int tm = 0; tm < 2; ++tm)
; #pragma unroll
;           for (int q = 0; q < 4; ++q) {
;             const int f = tm * 32 + 8 * q + 4 * hh;
;             const float4 g = *(const float4*)(p.k_norm_g + f);
;             uint2 o; o.x = pk_bf16(acc[tm][0][4 * q] * rk * g.x, acc[tm][0][4 * q + 1] * rk * g.y); o.y = pk_bf16(acc[tm][0][4 * q + 2] * rk * g.z, acc[tm][0][4 * q + 3] * rk * g.w);
;             *(uint2*)(kd + f * 2) = o;
;           }
; #pragma unroll
;         for (int q = 0; q < 4; ++q) {
;           uint2 o; o.x = pk_bf16(kp[4 * q], kp[4 * q + 1]); o.y = pk_bf16(kp[4 * q + 2], kp[4 * q + 3]);
;           *(uint2*)(kd + (64 + 8 * q + 4 * hh) * 2) = o;
;         }
; #pragma unroll
;         for (int tm = 2; tm < 4; ++tm)
; #pragma unroll
;           for (int i = 0; i < 16; ++i) *(bf16_t*)(vt_ + ((tm - 2) * 32 + crow(i, hh)) * 528 + tl * 2) = f2bf(acc[tm][0][i]);
;         lds_sync();
.LBB0_314:
	v_mov_b32_e32 v84, v146
	v_mov_b32_e32 v85, v147
	v_mov_b32_e32 v86, v148
	v_mov_b32_e32 v87, v149
	v_mov_b32_e32 v88, v150
	v_mov_b32_e32 v89, v151
	v_mov_b32_e32 v90, v152
	v_mov_b32_e32 v91, v153
	v_mov_b32_e32 v92, v154
	v_mov_b32_e32 v93, v155
	v_mov_b32_e32 v94, v156
	v_mov_b32_e32 v95, v157
	v_mov_b32_e32 v96, v158
	v_mov_b32_e32 v97, v159
	v_mov_b32_e32 v98, v160
	v_mov_b32_e32 v99, v161
	v_mov_b32_e32 v100, v162
	v_mov_b32_e32 v101, v163
	v_mov_b32_e32 v102, v164
	v_mov_b32_e32 v103, v165
	v_mov_b32_e32 v104, v166
	v_mov_b32_e32 v105, v167
	v_mov_b32_e32 v106, v168
	v_mov_b32_e32 v107, v169
	v_mov_b32_e32 v108, v170
	v_mov_b32_e32 v109, v171
	v_mov_b32_e32 v110, v172
	v_mov_b32_e32 v111, v173
	v_mov_b32_e32 v112, v174
	v_mov_b32_e32 v113, v175
	v_mov_b32_e32 v114, v176
	v_mov_b32_e32 v115, v177
	v_mov_b32_e32 v83, v82
	v_mul_f32_e32 v123, v0, v72
	v_mul_f32_e32 v124, v1, v72
	v_mul_f32_e32 v125, v2, v72
	v_mul_f32_e32 v126, v3, v72
	v_mul_f32_e32 v127, v4, v72
	v_mul_f32_e32 v128, v5, v72
	v_mul_f32_e32 v129, v6, v72
	v_mul_f32_e32 v130, v7, v72
	v_mul_f32_e32 v131, v8, v72
	v_mul_f32_e32 v132, v9, v72
	v_mul_f32_e32 v133, v10, v72
	v_mul_f32_e32 v134, v11, v72
	v_pk_mul_f32 v[0:1], v[48:49], v[82:83]
	v_pk_mul_f32 v[2:3], v[50:51], v[82:83]
	v_pk_mul_f32 v[4:5], v[52:53], v[82:83]
	v_pk_mul_f32 v[6:7], v[54:55], v[82:83]
	v_pk_mul_f32 v[8:9], v[56:57], v[82:83]
	v_pk_mul_f32 v[10:11], v[58:59], v[82:83]
	v_mul_f32_e32 v73, v16, v72
	v_mul_f32_e32 v116, v17, v72
	v_mul_f32_e32 v117, v18, v72
	v_mul_f32_e32 v118, v19, v72
	v_mul_f32_e32 v119, v20, v72
	v_mul_f32_e32 v120, v21, v72
	v_mul_f32_e32 v121, v22, v72
	v_mul_f32_e32 v122, v23, v72
	v_mul_f32_e32 v24, v24, v72
	v_mul_f32_e32 v25, v25, v72
	v_mul_f32_e32 v26, v26, v72
	v_mul_f32_e32 v27, v27, v72
	v_mul_f32_e32 v28, v28, v72
	v_mul_f32_e32 v29, v29, v72
	v_mul_f32_e32 v30, v30, v72
	v_mul_f32_e32 v31, v31, v72
	v_mul_f32_e32 v135, v12, v72
	v_mul_f32_e32 v136, v13, v72
	v_mul_f32_e32 v137, v14, v72
	v_mul_f32_e32 v72, v15, v72
	v_pk_mul_f32 v[12:13], v[60:61], v[82:83]
	v_pk_mul_f32 v[14:15], v[62:63], v[82:83]
	v_pk_mul_f32 v[16:17], v[64:65], v[82:83]
	v_pk_mul_f32 v[18:19], v[66:67], v[82:83]
	v_pk_mul_f32 v[20:21], v[68:69], v[82:83]
	v_pk_mul_f32 v[22:23], v[70:71], v[82:83]
	v_add_u32_e32 v138, v185, v187
	s_lshl_b32 s4, s90, 3
	s_or_b32 s6, s4, s57
	s_mul_i32 s5, s6, 0x900
	s_mul_hi_u32 s4, s6, 0x900
	s_add_u32 s5, s5, s42
	s_addc_u32 s4, s4, 0
	s_mulk_i32 s4, 0xc0
	s_mul_hi_u32 s7, s5, 0xc0
	s_add_i32 s7, s7, s4
	s_mulk_i32 s5, 0xc0
	s_add_u32 s4, s30, s5
	s_addc_u32 s5, s31, s7
	s_waitcnt vmcnt(7)
	v_pk_mul_f32 v[0:1], v[0:1], v[84:85]
	v_pk_mul_f32 v[2:3], v[2:3], v[86:87]
	s_waitcnt vmcnt(6)
	v_pk_mul_f32 v[4:5], v[4:5], v[88:89]
	v_pk_mul_f32 v[6:7], v[6:7], v[90:91]
	s_waitcnt vmcnt(5)
	v_pk_mul_f32 v[8:9], v[8:9], v[92:93]
	v_pk_mul_f32 v[10:11], v[10:11], v[94:95]
	s_waitcnt vmcnt(4)
	v_pk_mul_f32 v[12:13], v[12:13], v[96:97]
	v_pk_mul_f32 v[14:15], v[14:15], v[98:99]
	s_waitcnt vmcnt(3)
	v_pk_mul_f32 v[16:17], v[16:17], v[100:101]
	v_pk_mul_f32 v[18:19], v[18:19], v[102:103]
	s_waitcnt vmcnt(2)
	v_pk_mul_f32 v[20:21], v[20:21], v[104:105]
	v_pk_mul_f32 v[22:23], v[22:23], v[106:107]
	v_cvt_pk_bf16_f32 v0, v0, v1
	v_cvt_pk_bf16_f32 v1, v2, v3
	v_cvt_pk_bf16_f32 v2, v4, v5
	v_cvt_pk_bf16_f32 v3, v6, v7
	v_cvt_pk_bf16_f32 v4, v8, v9
	v_cvt_pk_bf16_f32 v5, v10, v11
	v_cvt_pk_bf16_f32 v6, v12, v13
	v_cvt_pk_bf16_f32 v7, v14, v15
	v_cvt_pk_bf16_f32 v8, v16, v17
	v_cvt_pk_bf16_f32 v9, v18, v19
	v_cvt_pk_bf16_f32 v10, v20, v21
	v_cvt_pk_bf16_f32 v11, v22, v23
	ds_write_b64 v207, v[2:3]
	ds_write_b64 v208, v[4:5]
	ds_write_b64 v209, v[6:7]
	ds_write_b64 v210, v[8:9]
	ds_write_b64 v211, v[10:11]
	v_pk_mul_f32 v[2:3], v[38:39], v[82:83]
	v_pk_mul_f32 v[4:5], v[36:37], v[82:83]
	s_waitcnt vmcnt(1)
	v_pk_mul_f32 v[2:3], v[2:3], v[108:109]
	v_pk_mul_f32 v[4:5], v[4:5], v[110:111]
	v_cvt_pk_bf16_f32 v2, v2, v3
	v_cvt_pk_bf16_f32 v3, v4, v5
	ds_write_b64 v212, v[2:3]
	v_pk_mul_f32 v[2:3], v[34:35], v[82:83]
	v_pk_mul_f32 v[4:5], v[32:33], v[82:83]
	s_waitcnt vmcnt(0)
	v_pk_mul_f32 v[2:3], v[2:3], v[112:113]
	v_pk_mul_f32 v[4:5], v[4:5], v[114:115]
	v_cvt_pk_bf16_f32 v2, v2, v3
	v_cvt_pk_bf16_f32 v3, v4, v5
	ds_write_b64 v213, v[2:3]
	v_cvt_pk_bf16_f32 v2, v76, v77
	v_cvt_pk_bf16_f32 v3, v78, v79
	ds_write2_b64 v138, v[0:1], v[2:3] offset1:16
	v_cvt_pk_bf16_f32 v0, v42, v43
	v_cvt_pk_bf16_f32 v1, v46, v47
	v_cvt_pk_bf16_f32 v2, v44, v45
	v_cvt_pk_bf16_f32 v3, v74, v75
	ds_write2_b64 v138, v[0:1], v[2:3] offset0:18 offset1:20
	v_cvt_pk_bf16_f32 v0, v40, v41
	v_cvt_pk_bf16_f32 v1, v80, v81
	ds_write_b64 v138, v[0:1] offset:176
	v_cvt_pk_bf16_f32 v0, v73, s0
	ds_write_b16 v204, v0 offset:53248
	v_cvt_pk_bf16_f32 v0, v116, s0
	ds_write_b16 v204, v0 offset:53776
	v_cvt_pk_bf16_f32 v0, v117, s0
	ds_write_b16 v204, v0 offset:54304
	v_cvt_pk_bf16_f32 v0, v118, s0
	ds_write_b16 v204, v0 offset:54832
	v_cvt_pk_bf16_f32 v0, v119, s0
	ds_write_b16 v204, v0 offset:57472
	v_cvt_pk_bf16_f32 v0, v120, s0
	ds_write_b16 v204, v0 offset:58000
	v_cvt_pk_bf16_f32 v0, v121, s0
	ds_write_b16 v204, v0 offset:58528
	v_cvt_pk_bf16_f32 v0, v122, s0
	ds_write_b16 v204, v0 offset:59056
	v_cvt_pk_bf16_f32 v0, v24, s0
	ds_write_b16 v204, v0 offset:61696
	v_cvt_pk_bf16_f32 v0, v25, s0
	ds_write_b16 v204, v0 offset:62224
	v_cvt_pk_bf16_f32 v0, v26, s0
	ds_write_b16 v204, v0 offset:62752
	v_cvt_pk_bf16_f32 v0, v27, s0
	ds_write_b16 v204, v0 offset:63280
	v_cvt_pk_bf16_f32 v0, v28, s0
	ds_write_b16 v205, v0 offset:12672
	v_cvt_pk_bf16_f32 v0, v29, s0
	ds_write_b16 v205, v0 offset:13200
	v_cvt_pk_bf16_f32 v0, v30, s0
	ds_write_b16 v205, v0 offset:13728
	v_cvt_pk_bf16_f32 v0, v31, s0
	ds_write_b16 v205, v0 offset:14256
	v_cvt_pk_bf16_f32 v0, v123, s0
	ds_write_b16 v205, v0 offset:16896
	v_cvt_pk_bf16_f32 v0, v124, s0
	ds_write_b16 v205, v0 offset:17424
	v_cvt_pk_bf16_f32 v0, v125, s0
	ds_write_b16 v205, v0 offset:17952
	v_cvt_pk_bf16_f32 v0, v126, s0
	ds_write_b16 v205, v0 offset:18480
	v_cvt_pk_bf16_f32 v0, v127, s0
	ds_write_b16 v205, v0 offset:21120
	v_cvt_pk_bf16_f32 v0, v128, s0
	ds_write_b16 v205, v0 offset:21648
	v_cvt_pk_bf16_f32 v0, v129, s0
	ds_write_b16 v205, v0 offset:22176
	v_cvt_pk_bf16_f32 v0, v130, s0
	ds_write_b16 v205, v0 offset:22704
	v_cvt_pk_bf16_f32 v0, v131, s0
	ds_write_b16 v205, v0 offset:25344
	v_cvt_pk_bf16_f32 v0, v132, s0
	ds_write_b16 v205, v0 offset:25872
	v_cvt_pk_bf16_f32 v0, v133, s0
	ds_write_b16 v205, v0 offset:26400
	v_cvt_pk_bf16_f32 v0, v134, s0
	ds_write_b16 v205, v0 offset:26928
	v_cvt_pk_bf16_f32 v0, v135, s0
	ds_write_b16 v205, v0 offset:29568
	v_cvt_pk_bf16_f32 v0, v136, s0
	ds_write_b16 v205, v0 offset:30096
	v_cvt_pk_bf16_f32 v0, v137, s0
	ds_write_b16 v205, v0 offset:30624
	v_cvt_pk_bf16_f32 v0, v72, s0
	ds_write_b16 v205, v0 offset:31152
	v_mov_b32_e32 v10, v220
	s_waitcnt lgkmcnt(0)
	s_barrier
; DI int tid_() { int t = threadIdx.x; asm volatile("" : "+v"(t)); return t; }
; DI void lds_sync() { wait_lgkm0(); bar_(); }
; DI void phase3(const Params& p, char* smem) {
;     ...
;         lds_sync();
;         const int tc_ = tid_();
;         bf16_t* Kg = p.K + ((size_t)(b * NH + hd) * NKEY + key0) * QKD;
; #pragma unroll
;         for (int i = 0; i < 6; ++i) {
;           const int id = tc_ + NTH * i, row = id / 12, ch = id % 12;
;           *(uint4*)(Kg + row * QKD + ch * 8) = *(const uint4*)(kt_ + row * 208 + ch * 16);
;         }
;         bf16_t* Vg = p.Vt + (size_t)(b * NH + hd) * VD * NKEY + key0;
; #pragma unroll
;         for (int i = 0; i < 4; ++i) {
;           const int row = (tc_ >> 5) + 16 * i, ch = tc_ & 31;
;           *(uint4*)(Vg + (size_t)row * NKEY + ch * 8) = *(const uint4*)(vt_ + row * 528 + ch * 16);
;         }
;         lds_sync();
	s_nop 0
	v_mul_hi_i32 v0, v10, s86
	v_lshrrev_b32_e32 v1, 31, v0
	v_ashrrev_i32_e32 v0, 1, v0
	v_add_u32_e32 v0, v0, v1
	v_mul_lo_u32 v1, v0, 12
	v_sub_u32_e32 v2, v10, v1
	v_mul_lo_u32 v1, v0, s65
	v_mul_lo_u32 v0, v0, s66
	v_lshl_add_u32 v4, v2, 4, v1
	v_ashrrev_i32_e32 v1, 31, v0
	v_lshlrev_b32_e32 v2, 3, v2
	v_lshl_add_u64 v[0:1], v[0:1], 1, s[4:5]
	v_ashrrev_i32_e32 v3, 31, v2
	v_lshl_add_u64 v[8:9], v[2:3], 1, v[0:1]
	ds_read_b128 v[0:3], v4
	v_add_u32_e32 v4, 0x200, v10
	v_mul_hi_i32 v5, v4, s86
	v_lshrrev_b32_e32 v6, 31, v5
	v_ashrrev_i32_e32 v5, 1, v5
	v_add_u32_e32 v11, v5, v6
	v_mul_lo_u32 v5, v11, 12
	v_sub_u32_e32 v12, v4, v5
	v_mul_lo_u32 v4, v11, s65
	v_lshl_add_u32 v4, v12, 4, v4
	ds_read_b128 v[4:7], v4
	s_waitcnt lgkmcnt(1)
	global_store_dwordx4 v[8:9], v[0:3], off
	v_ashrrev_i32_e32 v14, 5, v10
	s_nop 0
	v_mul_lo_u32 v0, v11, s66
	v_ashrrev_i32_e32 v1, 31, v0
	v_lshlrev_b32_e32 v2, 3, v12
	v_lshl_add_u64 v[0:1], v[0:1], 1, s[4:5]
	v_ashrrev_i32_e32 v3, 31, v2
	v_lshl_add_u64 v[0:1], v[2:3], 1, v[0:1]
	s_waitcnt lgkmcnt(0)
	global_store_dwordx4 v[0:1], v[4:7], off
	v_add_u32_e32 v0, 0x400, v10
	v_mul_hi_i32 v1, v0, s86
	v_lshrrev_b32_e32 v2, 31, v1
	v_ashrrev_i32_e32 v1, 1, v1
	v_add_u32_e32 v1, v1, v2
	v_mul_lo_u32 v2, v1, 12
	v_sub_u32_e32 v2, v0, v2
	v_mul_lo_u32 v0, v1, s65
	v_lshl_add_u32 v4, v2, 4, v0
	v_mul_lo_u32 v0, v1, s66
	v_ashrrev_i32_e32 v1, 31, v0
	v_lshlrev_b32_e32 v2, 3, v2
	v_lshl_add_u64 v[0:1], v[0:1], 1, s[4:5]
	v_ashrrev_i32_e32 v3, 31, v2
	v_lshl_add_u64 v[8:9], v[2:3], 1, v[0:1]
	ds_read_b128 v[0:3], v4
	v_add_u32_e32 v4, 0x600, v10
	v_mul_hi_i32 v5, v4, s86
	v_lshrrev_b32_e32 v6, 31, v5
	v_ashrrev_i32_e32 v5, 1, v5
	v_add_u32_e32 v11, v5, v6
	v_mul_lo_u32 v5, v11, 12
	v_sub_u32_e32 v12, v4, v5
	v_mul_lo_u32 v4, v11, s65
	v_lshl_add_u32 v4, v12, 4, v4
	ds_read_b128 v[4:7], v4
	s_waitcnt lgkmcnt(1)
	global_store_dwordx4 v[8:9], v[0:3], off
	s_nop 1
	v_mul_lo_u32 v0, v11, s66
	v_ashrrev_i32_e32 v1, 31, v0
	v_lshlrev_b32_e32 v2, 3, v12
	v_lshl_add_u64 v[0:1], v[0:1], 1, s[4:5]
	v_ashrrev_i32_e32 v3, 31, v2
	v_lshl_add_u64 v[0:1], v[2:3], 1, v[0:1]
	s_waitcnt lgkmcnt(0)
	global_store_dwordx4 v[0:1], v[4:7], off
	v_add_u32_e32 v0, 0x800, v10
	v_mul_hi_i32 v1, v0, s86
	v_lshrrev_b32_e32 v2, 31, v1
	v_ashrrev_i32_e32 v1, 1, v1
	v_add_u32_e32 v1, v1, v2
	v_mul_lo_u32 v2, v1, 12
	v_sub_u32_e32 v2, v0, v2
	v_mul_lo_u32 v0, v1, s65
	v_lshl_add_u32 v4, v2, 4, v0
	v_mul_lo_u32 v0, v1, s66
	v_ashrrev_i32_e32 v1, 31, v0
	v_lshlrev_b32_e32 v2, 3, v2
	v_lshl_add_u64 v[0:1], v[0:1], 1, s[4:5]
	v_ashrrev_i32_e32 v3, 31, v2
	v_lshl_add_u64 v[8:9], v[2:3], 1, v[0:1]
	ds_read_b128 v[0:3], v4
	v_add_u32_e32 v4, 0xa00, v10
	v_mul_hi_i32 v5, v4, s86
	v_lshrrev_b32_e32 v6, 31, v5
	v_ashrrev_i32_e32 v5, 1, v5
	v_add_u32_e32 v11, v5, v6
	v_mul_lo_u32 v5, v11, 12
	v_sub_u32_e32 v12, v4, v5
	v_mul_lo_u32 v4, v11, s65
	v_lshl_add_u32 v4, v12, 4, v4
	ds_read_b128 v[4:7], v4
	s_waitcnt lgkmcnt(1)
	global_store_dwordx4 v[8:9], v[0:3], off
	s_nop 1
	v_mul_lo_u32 v0, v11, s66
	v_ashrrev_i32_e32 v1, 31, v0
	v_lshlrev_b32_e32 v2, 3, v12
	v_lshl_add_u64 v[0:1], v[0:1], 1, s[4:5]
	v_ashrrev_i32_e32 v3, 31, v2
	s_mul_hi_u32 s4, s6, 0x48000
	s_mul_i32 s6, s6, 0x48000
	v_lshl_add_u64 v[0:1], v[2:3], 1, v[0:1]
	s_add_u32 s5, s40, s6
	s_waitcnt lgkmcnt(0)
	global_store_dwordx4 v[0:1], v[4:7], off
	s_addc_u32 s6, s41, s4
	s_lshl_b32 s4, s42, 1
	v_lshlrev_b32_e32 v0, 4, v10
	s_add_u32 s4, s5, s4
	v_and_b32_e32 v188, 0x1f0, v0
	s_addc_u32 s5, s6, 0
	v_mad_u64_u32 v[8:9], s[6:7], v14, s78, v[188:189]
	ds_read_b128 v[0:3], v8 offset:53248
	ds_read_b128 v[4:7], v8 offset:61696
	v_lshl_add_u64 v[10:11], s[4:5], 0, v[188:189]
	v_mad_i64_i32 v[12:13], s[4:5], v14, s88, v[10:11]
	s_waitcnt lgkmcnt(1)
	global_store_dwordx4 v[12:13], v[0:3], off
	s_nop 1
	v_add_u32_e32 v0, 16, v14
	v_mad_i64_i32 v[0:1], s[4:5], v0, s88, v[10:11]
	s_waitcnt lgkmcnt(0)
	global_store_dwordx4 v[0:1], v[4:7], off
	v_add_u32_e32 v0, 0x11200, v8
	ds_read_b128 v[0:3], v0
	v_add_u32_e32 v4, 32, v14
	v_mad_i64_i32 v[12:13], s[4:5], v4, s88, v[10:11]
	v_add_u32_e32 v4, 0x13300, v8
	ds_read_b128 v[4:7], v4
	s_waitcnt lgkmcnt(1)
	global_store_dwordx4 v[12:13], v[0:3], off
	s_nop 1
	v_add_u32_e32 v0, 48, v14
	v_mad_i64_i32 v[0:1], s[4:5], v0, s88, v[10:11]
	s_waitcnt lgkmcnt(0)
	global_store_dwordx4 v[0:1], v[4:7], off
	s_waitcnt lgkmcnt(0)
	s_barrier

; DI void wait_vm0() { asm volatile("s_waitcnt vmcnt(0)" ::: "memory"); }
; DI void bar_() { __builtin_amdgcn_s_barrier(); }
; #define GLDS(gp, lp) __builtin_amdgcn_global_load_lds((const unsigned*)(gp), (__attribute__((address_space(3))) unsigned*)(lp), 16, 0, 0)
; #define SB_ __builtin_amdgcn_sched_barrier(0)
; #define LOADF(A_, B_, ks) do { const int po_ = (((ks) * 2 + hh) ^ sw) * 16; \
;       _Pragma("unroll") for (int tm = 0; tm < TM; ++tm) A_[tm] = *(const bf16x8*)(As + tm * 32 * LDR + po_); \
;       _Pragma("unroll") for (int tn = 0; tn < TN; ++tn) B_[tn] = *(const bf16x8*)(Bs + tn * 32 * LDR + po_); } while (0)
; template <int TM, int TN, int WM, int WN, bool SUMSQ, int NST, class AF, class BF, class AFN, class BFN>
; DI void gemm8x(f32x16 (&acc)[TM][TN], AF arow, BF brow, int K, char* smem, float& sumsq, bool pre, bool hasNext, AFN arowN, BFN browN) {
;     ...
;     LOADF(a0, b0, 0);
;     LOADF(a1, b1, 1);
;     SB_;
;     if (issue) { if (a0v) GLDS(q0, l_); if (a1v) GLDS(q1, l_ + 8192); }
;     SB_;
;     __builtin_amdgcn_s_setprio(1);
;     MMF(a0, b0);
;     LOADF(a0, b0, 2);
;     SB_;
;     if (issue) { if (a2v) GLDS(q2, l_ + 16384); if (a3v) GLDS(q3, l_ + 24576); }
;     SB_;
;     MMF(a1, b1);
;     LOADF(a1, b1, 3);
;     SB_;
;     if (issue) { if (b0v) GLDS(s0, m_); if (b1v) GLDS(s1, m_ + 8192); }
;     SB_;
;     MMF(a0, b0);
;     SB_;
;     if (issue) { if (b2v) GLDS(s2, m_ + 16384); if (b3v) GLDS(s3, m_ + 24576); }
;     SB_;
;     MMF(a1, b1);
;     __builtin_amdgcn_s_setprio(0);
;   };
;   int sc_ = 0;
;   for (int kt = 0; kt < nk - 1; ++kt) {
;     SB_;
;     if (NST == 2) {
;       const int ko = (kt + 1) * 64;
;       compute(smem + (kt & 1) * STAGE, smem + ((kt + 1) & 1) * STAGE, true, pa0 + ko, pa1 + ko, pa2 + ko, pa3 + ko, pb0 + ko, pb1 + ko, pb2 + ko, pb3 + ko);
;       SB_;
;       wait_vm0(); bar_();
.LBB0_522:
	s_or_b64 exec, exec, s[6:7]
	v_lshlrev_b32_e32 v128, 16, v68
	v_and_b32_e32 v68, 0xffff0000, v68
	v_mul_f32_e32 v68, v68, v68
	v_lshlrev_b32_e32 v129, 16, v69
	v_fmac_f32_e32 v68, v128, v128
	v_and_b32_e32 v69, 0xffff0000, v69
	v_fmac_f32_e32 v68, v129, v129
	v_lshlrev_b32_e32 v130, 16, v70
	v_fmac_f32_e32 v68, v69, v69
	v_lshlrev_b32_e32 v69, 16, v64
	v_and_b32_e32 v64, 0xffff0000, v64
	v_and_b32_e32 v70, 0xffff0000, v70
	v_fmac_f32_e32 v68, v130, v130
	v_mul_f32_e32 v64, v64, v64
	v_lshlrev_b32_e32 v131, 16, v71
	v_fmac_f32_e32 v68, v70, v70
	v_lshlrev_b32_e32 v70, 16, v65
	v_fmac_f32_e32 v64, v69, v69
	v_and_b32_e32 v71, 0xffff0000, v71
	v_fmac_f32_e32 v68, v131, v131
	v_and_b32_e32 v65, 0xffff0000, v65
	v_fmac_f32_e32 v64, v70, v70
	v_fmac_f32_e32 v68, v71, v71
	v_lshlrev_b32_e32 v71, 16, v66
	v_fmac_f32_e32 v64, v65, v65
	v_and_b32_e32 v66, 0xffff0000, v66
	v_fmac_f32_e32 v64, v71, v71
	v_lshlrev_b32_e32 v128, 16, v67
	v_fmac_f32_e32 v64, v66, v66
	v_and_b32_e32 v66, 0xffff0000, v72
	v_and_b32_e32 v67, 0xffff0000, v67
	v_fmac_f32_e32 v64, v128, v128
	v_lshlrev_b32_e32 v65, 16, v72
	v_mul_f32_e32 v66, v66, v66
	v_fmac_f32_e32 v64, v67, v67
	v_lshlrev_b32_e32 v67, 16, v73
	v_fmac_f32_e32 v66, v65, v65
	v_add_f32_e32 v64, v68, v64
	v_and_b32_e32 v68, 0xffff0000, v73
	v_fmac_f32_e32 v66, v67, v67
	v_lshlrev_b32_e32 v69, 16, v74
	v_fmac_f32_e32 v66, v68, v68
	v_and_b32_e32 v70, 0xffff0000, v74
	v_fmac_f32_e32 v66, v69, v69
	v_lshlrev_b32_e32 v71, 16, v75
	v_fmac_f32_e32 v66, v70, v70
	v_and_b32_e32 v72, 0xffff0000, v75
	v_fmac_f32_e32 v66, v71, v71
	v_fmac_f32_e32 v66, v72, v72
	v_add_f32_e32 v64, v64, v66
	v_and_b32_e32 v66, 0xffff0000, v76
	v_lshlrev_b32_e32 v65, 16, v76
	v_mul_f32_e32 v66, v66, v66
	v_lshlrev_b32_e32 v67, 16, v77
	v_fmac_f32_e32 v66, v65, v65
	v_and_b32_e32 v68, 0xffff0000, v77
	v_fmac_f32_e32 v66, v67, v67
	v_lshlrev_b32_e32 v69, 16, v78
	v_fmac_f32_e32 v66, v68, v68
	v_and_b32_e32 v70, 0xffff0000, v78
	v_fmac_f32_e32 v66, v69, v69
	v_lshlrev_b32_e32 v71, 16, v79
	v_fmac_f32_e32 v66, v70, v70
	v_and_b32_e32 v72, 0xffff0000, v79
	v_fmac_f32_e32 v66, v71, v71
	v_fmac_f32_e32 v66, v72, v72
	v_add_f32_e32 v64, v64, v66
	v_and_b32_e32 v66, 0xffff0000, v84
	v_lshlrev_b32_e32 v65, 16, v84
	v_mul_f32_e32 v66, v66, v66
	v_lshlrev_b32_e32 v67, 16, v85
	v_fmac_f32_e32 v66, v65, v65
	v_and_b32_e32 v68, 0xffff0000, v85
	v_fmac_f32_e32 v66, v67, v67
	v_lshlrev_b32_e32 v69, 16, v86
	v_fmac_f32_e32 v66, v68, v68
	v_and_b32_e32 v70, 0xffff0000, v86
	v_fmac_f32_e32 v66, v69, v69
	v_lshlrev_b32_e32 v71, 16, v87
	v_fmac_f32_e32 v66, v70, v70
	v_and_b32_e32 v72, 0xffff0000, v87
	v_fmac_f32_e32 v66, v71, v71
	v_fmac_f32_e32 v66, v72, v72
	v_add_f32_e32 v64, v64, v66
	v_and_b32_e32 v66, 0xffff0000, v80
	v_lshlrev_b32_e32 v65, 16, v80
	v_mul_f32_e32 v66, v66, v66
	v_lshlrev_b32_e32 v67, 16, v81
	v_fmac_f32_e32 v66, v65, v65
	v_and_b32_e32 v68, 0xffff0000, v81
	v_fmac_f32_e32 v66, v67, v67
	v_lshlrev_b32_e32 v69, 16, v82
	v_fmac_f32_e32 v66, v68, v68
	v_and_b32_e32 v70, 0xffff0000, v82
	v_fmac_f32_e32 v66, v69, v69
	v_lshlrev_b32_e32 v71, 16, v83
	v_fmac_f32_e32 v66, v70, v70
	v_and_b32_e32 v72, 0xffff0000, v83
	v_fmac_f32_e32 v66, v71, v71
	v_fmac_f32_e32 v66, v72, v72
	v_add_f32_e32 v64, v64, v66
	v_and_b32_e32 v66, 0xffff0000, v88
	v_lshlrev_b32_e32 v65, 16, v88
	v_mul_f32_e32 v66, v66, v66
	v_lshlrev_b32_e32 v67, 16, v89
	v_fmac_f32_e32 v66, v65, v65
	v_and_b32_e32 v68, 0xffff0000, v89
	v_fmac_f32_e32 v66, v67, v67
	v_lshlrev_b32_e32 v69, 16, v90
	v_fmac_f32_e32 v66, v68, v68
	v_and_b32_e32 v70, 0xffff0000, v90
	v_fmac_f32_e32 v66, v69, v69
	v_lshlrev_b32_e32 v71, 16, v91
	v_fmac_f32_e32 v66, v70, v70
	v_and_b32_e32 v72, 0xffff0000, v91
	v_fmac_f32_e32 v66, v71, v71
	v_fmac_f32_e32 v66, v72, v72
	v_add_f32_e32 v64, v64, v66
	v_and_b32_e32 v66, 0xffff0000, v92
	v_lshlrev_b32_e32 v65, 16, v92
	v_mul_f32_e32 v66, v66, v66
	v_lshlrev_b32_e32 v67, 16, v93
	v_fmac_f32_e32 v66, v65, v65
	v_and_b32_e32 v68, 0xffff0000, v93
	v_fmac_f32_e32 v66, v67, v67
	v_lshlrev_b32_e32 v69, 16, v94
	v_fmac_f32_e32 v66, v68, v68
	v_and_b32_e32 v70, 0xffff0000, v94
	v_fmac_f32_e32 v66, v69, v69
	v_lshlrev_b32_e32 v71, 16, v95
	v_fmac_f32_e32 v66, v70, v70
	v_and_b32_e32 v72, 0xffff0000, v95
	v_fmac_f32_e32 v66, v71, v71
	v_fmac_f32_e32 v66, v72, v72
	v_add_f32_e32 v64, v64, v66
	v_and_b32_e32 v66, 0xffff0000, v124
	v_lshlrev_b32_e32 v65, 16, v124
	v_mul_f32_e32 v66, v66, v66
	v_lshlrev_b32_e32 v67, 16, v125
	v_fmac_f32_e32 v66, v65, v65
	v_and_b32_e32 v68, 0xffff0000, v125
	v_fmac_f32_e32 v66, v67, v67
	v_lshlrev_b32_e32 v69, 16, v126
	v_fmac_f32_e32 v66, v68, v68
	v_and_b32_e32 v70, 0xffff0000, v126
	v_fmac_f32_e32 v66, v69, v69
	v_lshlrev_b32_e32 v71, 16, v127
	v_fmac_f32_e32 v66, v70, v70
	v_and_b32_e32 v72, 0xffff0000, v127
	v_fmac_f32_e32 v66, v71, v71
	v_fmac_f32_e32 v66, v72, v72
	v_add_f32_e32 v64, v64, v66
	v_and_b32_e32 v66, 0xffff0000, v108
	v_lshlrev_b32_e32 v65, 16, v108
	v_mul_f32_e32 v66, v66, v66
	v_lshlrev_b32_e32 v67, 16, v109
	v_fmac_f32_e32 v66, v65, v65
	v_and_b32_e32 v68, 0xffff0000, v109
	v_fmac_f32_e32 v66, v67, v67
	v_lshlrev_b32_e32 v69, 16, v110
	v_fmac_f32_e32 v66, v68, v68
	v_and_b32_e32 v70, 0xffff0000, v110
	v_fmac_f32_e32 v66, v69, v69
	v_lshlrev_b32_e32 v71, 16, v111
	v_fmac_f32_e32 v66, v70, v70
	v_and_b32_e32 v72, 0xffff0000, v111
	v_fmac_f32_e32 v66, v71, v71
	v_fmac_f32_e32 v66, v72, v72
	v_add_f32_e32 v64, v64, v66
	v_and_b32_e32 v66, 0xffff0000, v120
	v_lshlrev_b32_e32 v65, 16, v120
	v_mul_f32_e32 v66, v66, v66
	v_lshlrev_b32_e32 v67, 16, v121
	v_fmac_f32_e32 v66, v65, v65
	v_and_b32_e32 v68, 0xffff0000, v121
	v_fmac_f32_e32 v66, v67, v67
	v_lshlrev_b32_e32 v69, 16, v122
	v_fmac_f32_e32 v66, v68, v68
	v_and_b32_e32 v70, 0xffff0000, v122
	v_fmac_f32_e32 v66, v69, v69
	v_lshlrev_b32_e32 v71, 16, v123
	v_fmac_f32_e32 v66, v70, v70
	v_and_b32_e32 v72, 0xffff0000, v123
	v_fmac_f32_e32 v66, v71, v71
	v_fmac_f32_e32 v66, v72, v72
	v_add_f32_e32 v66, v64, v66
	v_and_b32_e32 v65, 0xffff0000, v100
	v_lshlrev_b32_e32 v64, 16, v100
	v_mul_f32_e32 v69, v65, v65
	v_mfma_f32_32x32x16_bf16 v[48:63], v[116:119], v[100:103], v[48:63]
	v_lshlrev_b32_e32 v67, 16, v101
	v_fmac_f32_e32 v69, v64, v64
	v_and_b32_e32 v68, 0xffff0000, v101
	v_fmac_f32_e32 v69, v67, v67
	v_and_b32_e32 v64, 0xffff0000, v102
	v_lshlrev_b32_e32 v65, 16, v102
	v_fmac_f32_e32 v69, v68, v68
	v_mfma_f32_32x32x16_bf16 v[32:47], v[112:115], v[100:103], v[32:47]
	v_mul_f32_e64 v64, v64, v64
	v_mul_f32_e64 v65, v65, v65
	v_add_f32_e32 v65, v65, v69
	v_add_f32_e32 v67, v64, v65
	v_and_b32_e32 v64, 0xffff0000, v103
	v_lshlrev_b32_e32 v65, 16, v103
	v_pk_mul_f32 v[64:65], v[64:65], v[64:65]
	v_mfma_f32_32x32x16_bf16 v[16:31], v[104:107], v[100:103], v[16:31]
	v_add_f32_e32 v65, v65, v67
	v_add_f32_e32 v64, v64, v65
	v_add_f32_e32 v118, v66, v64
	v_mfma_f32_32x32x16_bf16 v[0:15], v[96:99], v[100:103], v[0:15]
	s_setprio 0
	s_waitcnt vmcnt(0)
	s_barrier
; DI void lds_sync() { wait_lgkm0(); bar_(); }
; #define GLDS(gp, lp) __builtin_amdgcn_global_load_lds((const unsigned*)(gp), (__attribute__((address_space(3))) unsigned*)(lp), 16, 0, 0)
; #define SB_ __builtin_amdgcn_sched_barrier(0)
; #define LOADF(A_, B_, ks) do { const int po_ = (((ks) * 2 + hh) ^ sw) * 16; \
;       _Pragma("unroll") for (int tm = 0; tm < TM; ++tm) A_[tm] = *(const bf16x8*)(As + tm * 32 * LDR + po_); \
;       _Pragma("unroll") for (int tn = 0; tn < TN; ++tn) B_[tn] = *(const bf16x8*)(Bs + tn * 32 * LDR + po_); } while (0)
; template <int TM, int TN, int WM, int WN, bool SUMSQ, int NST, class AF, class BF, class AFN, class BFN>
; DI void gemm8x(f32x16 (&acc)[TM][TN], AF arow, BF brow, int K, char* smem, float& sumsq, bool pre, bool hasNext, AFN arowN, BFN browN) {
;     ...
;     LOADF(a0, b0, 0);
;     LOADF(a1, b1, 1);
;     SB_;
;     if (issue) { if (a0v) GLDS(q0, l_); if (a1v) GLDS(q1, l_ + 8192); }
;     SB_;
;     __builtin_amdgcn_s_setprio(1);
;     MMF(a0, b0);
;     LOADF(a0, b0, 2);
;     SB_;
;     if (issue) { if (a2v) GLDS(q2, l_ + 16384); if (a3v) GLDS(q3, l_ + 24576); }
;     SB_;
;     MMF(a1, b1);
;     LOADF(a1, b1, 3);
;     SB_;
;     if (issue) { if (b0v) GLDS(s0, m_); if (b1v) GLDS(s1, m_ + 8192); }
;     SB_;
;     MMF(a0, b0);
;     SB_;
;     if (issue) { if (b2v) GLDS(s2, m_ + 16384); if (b3v) GLDS(s3, m_ + 24576); }
;     SB_;
;     MMF(a1, b1);
;     __builtin_amdgcn_s_setprio(0);
;     ...
;     SB_;
;     compute(smem + ((nk - 1) & 1) * STAGE, smem, hasNext, q0, q1, q2, q3, s0, s1, s2, s3);
;     SB_;
;     lds_sync();
	ds_read_b128 v[64:67], v162 offset:49152
	ds_read_b128 v[68:71], v162 offset:53248
	ds_read_b128 v[72:75], v162 offset:57344
	ds_read_b128 v[76:79], v162 offset:61440
	ds_read_b128 v[80:83], v165 offset:16384
	ds_read_b128 v[84:87], v163 offset:49152
	ds_read_b128 v[88:91], v163 offset:53248
	ds_read_b128 v[92:95], v163 offset:57344
	ds_read_b128 v[96:99], v163 offset:61440
	ds_read_b128 v[100:103], v166 offset:16384
	s_setprio 1
	s_waitcnt lgkmcnt(0)
	v_mfma_f32_32x32x16_bf16 v[48:63], v[64:67], v[80:83], v[48:63]
	v_mfma_f32_32x32x16_bf16 v[32:47], v[68:71], v[80:83], v[32:47]
	v_mfma_f32_32x32x16_bf16 v[16:31], v[72:75], v[80:83], v[16:31]
	ds_read_b128 v[64:67], v161 offset:49152
	ds_read_b128 v[68:71], v161 offset:53248
	ds_read_b128 v[72:75], v161 offset:57344
	ds_read_b128 v[104:107], v161 offset:61440
	ds_read_b128 v[108:111], v167 offset:16384
	v_mfma_f32_32x32x16_bf16 v[0:15], v[76:79], v[80:83], v[0:15]
	v_and_b32_e32 v79, 0xffff0000, v100
	v_and_b32_e32 v78, 0xffff0000, v80
	v_lshlrev_b32_e32 v77, 16, v100
	v_lshlrev_b32_e32 v76, 16, v80
	v_mul_f32_e64 v78, v78, v78
	v_mul_f32_e64 v79, v79, v79
	v_lshlrev_b32_e32 v113, 16, v101
	v_lshlrev_b32_e32 v112, 16, v81
	v_pk_fma_f32 v[76:77], v[76:77], v[76:77], v[78:79]
	v_and_b32_e32 v115, 0xffff0000, v101
	v_and_b32_e32 v114, 0xffff0000, v81
	v_pk_fma_f32 v[76:77], v[112:113], v[112:113], v[76:77]
	v_lshlrev_b32_e32 v81, 16, v102
	v_lshlrev_b32_e32 v80, 16, v82
	v_pk_fma_f32 v[76:77], v[114:115], v[114:115], v[76:77]
	v_mfma_f32_32x32x16_bf16 v[48:63], v[84:87], v[100:103], v[48:63]
	v_and_b32_e32 v85, 0xffff0000, v102
	v_and_b32_e32 v84, 0xffff0000, v82
	v_fma_f32 v76, v80, v80, v76
	v_fma_f32 v77, v81, v81, v77
	v_lshlrev_b32_e32 v87, 16, v103
	v_lshlrev_b32_e32 v86, 16, v83
	v_pk_fma_f32 v[76:77], v[84:85], v[84:85], v[76:77]
	v_and_b32_e32 v117, 0xffff0000, v103
	v_and_b32_e32 v116, 0xffff0000, v83
	v_pk_fma_f32 v[76:77], v[86:87], v[86:87], v[76:77]
	v_mfma_f32_32x32x16_bf16 v[32:47], v[88:91], v[100:103], v[32:47]
	v_fma_f32 v76, v116, v116, v76
	v_fma_f32 v77, v117, v117, v77
	v_add_f32_e32 v76, v118, v76
	v_add_f32_e32 v112, v76, v77
	v_mfma_f32_32x32x16_bf16 v[16:31], v[92:95], v[100:103], v[16:31]
	ds_read_b128 v[76:79], v160 offset:49152
	ds_read_b128 v[80:83], v160 offset:53248
	ds_read_b128 v[84:87], v160 offset:57344
	ds_read_b128 v[88:91], v160 offset:61440
	ds_read_b128 v[92:95], v164 offset:16384
	v_mfma_f32_32x32x16_bf16 v[0:15], v[96:99], v[100:103], v[0:15]
	s_waitcnt lgkmcnt(0)
	v_mfma_f32_32x32x16_bf16 v[48:63], v[64:67], v[108:111], v[48:63]
	v_mfma_f32_32x32x16_bf16 v[32:47], v[68:71], v[108:111], v[32:47]
	v_mfma_f32_32x32x16_bf16 v[16:31], v[72:75], v[108:111], v[16:31]
	v_mfma_f32_32x32x16_bf16 v[0:15], v[104:107], v[108:111], v[0:15]
	v_and_b32_e32 v67, 0xffff0000, v92
	v_and_b32_e32 v66, 0xffff0000, v108
	v_lshlrev_b32_e32 v64, 16, v108
	v_lshlrev_b32_e32 v65, 16, v92
	v_mul_f32_e64 v66, v66, v66
	v_mul_f32_e64 v67, v67, v67
	v_lshlrev_b32_e32 v68, 16, v109
	v_lshlrev_b32_e32 v69, 16, v93
	v_pk_fma_f32 v[64:65], v[64:65], v[64:65], v[66:67]
	v_mfma_f32_32x32x16_bf16 v[48:63], v[76:79], v[92:95], v[48:63]
	v_and_b32_e32 v71, 0xffff0000, v93
	v_and_b32_e32 v70, 0xffff0000, v109
	v_fma_f32 v64, v68, v68, v64
	v_fma_f32 v65, v69, v69, v65
	v_lshlrev_b32_e32 v72, 16, v110
	v_lshlrev_b32_e32 v73, 16, v94
	v_pk_fma_f32 v[64:65], v[70:71], v[70:71], v[64:65]
	v_and_b32_e32 v75, 0xffff0000, v94
	v_mfma_f32_32x32x16_bf16 v[32:47], v[80:83], v[92:95], v[32:47]
	v_and_b32_e32 v74, 0xffff0000, v110
	v_fma_f32 v64, v72, v72, v64
	v_fma_f32 v65, v73, v73, v65
	v_lshlrev_b32_e32 v76, 16, v111
	v_lshlrev_b32_e32 v77, 16, v95
	v_pk_fma_f32 v[64:65], v[74:75], v[74:75], v[64:65]
	v_and_b32_e32 v79, 0xffff0000, v95
	v_and_b32_e32 v78, 0xffff0000, v111
	v_mfma_f32_32x32x16_bf16 v[16:31], v[84:87], v[92:95], v[16:31]
	v_fma_f32 v64, v76, v76, v64
	v_fma_f32 v65, v77, v77, v65
	v_fma_f32 v64, v78, v78, v64
	v_fma_f32 v65, v79, v79, v65
	v_add_f32_e32 v64, v112, v64
	v_add_f32_e32 v66, v64, v65
	v_mfma_f32_32x32x16_bf16 v[0:15], v[88:91], v[92:95], v[0:15]
	s_setprio 0
	v_mad_i64_i32 v[64:65], s[4:5], s56, v184, 0
	v_lshl_add_u64 v[64:65], v[64:65], 1, s[16:17]
	v_lshlrev_b32_e32 v188, 1, v186
	v_lshl_add_u64 v[64:65], v[64:65], 0, v[188:189]
	s_waitcnt lgkmcnt(0)
	s_barrier
; DI float bf_lo(unsigned u) { return __uint_as_float(u << 16); }
; DI float bf_hi(unsigned u) { return __uint_as_float(u & 0xffff0000u); }
; DI int crow(int i, int hh) { return (i & 3) + 8 * (i >> 2) + 4 * hh; }
; DI void phase3(const Params& p, char* smem) {
;     ...
;       sumsq += __shfl_xor(sumsq, 32);
;       const float ra = rsqrtf(sumsq * (1.f / KVL) + EPS);
;       const int tl = w * 32 + r;
;       const int key = key0 + tl;
;       float kp[16];
; #pragma unroll
;       for (int q = 0; q < 4; ++q) {
;         const uint2 u = *(const uint2*)(kpeb + (size_t)tl * ldb + 8 * q + 4 * hh);
;         kp[4 * q + 0] = bf_lo(u.x); kp[4 * q + 1] = bf_hi(u.x); kp[4 * q + 2] = bf_lo(u.y); kp[4 * q + 3] = bf_hi(u.y);
;       }
;       float ss = 0.f;
; #pragma unroll
;       for (int tm = 0; tm < 4; ++tm)
; #pragma unroll
;         for (int i = 0; i < 16; ++i) { const float v = acc[tm][0][i] * ra; acc[tm][0][i] = v; if (tm < 2) ss += v * v; }
; #pragma unroll
;       for (int i = 0; i < 16; ++i) ss += kp[i] * kp[i];
;       ss += __shfl_xor(ss, 32);
;       const float rk = rsqrtf(ss * (1.f / QKD) + EPS);
; #pragma unroll
;       for (int i = 0; i < 16; ++i) kp[i] *= rk * p.k_norm_g[64 + crow(i, hh)];
;       if (lat) {
;         const int pos = key;
;         const float* tr = p.ropeTab + ((pos >> 6) * 8 + 4 * hh) * 2;
;         const float* tc = p.ropeTab + ((pos & 63) * 8 + 4 * hh) * 2;
; #pragma unroll
;         for (int i = 0; i < 4; ++i) { rope_pair(kp[i], kp[i + 4], tr + 2 * i); rope_pair(kp[8 + i], kp[12 + i], tc + 2 * i); }
;       }
;       {
;         char* kt_ = smem; char* vt_ = smem + 256 * 208;
;         char* kd = kt_ + tl * 208;
; #pragma unroll
;         for (int tm = 0; tm < 2; ++tm)
; #pragma unroll
;           for (int q = 0; q < 4; ++q) {
;             const int f = tm * 32 + 8 * q + 4 * hh;
;             const float4 g = *(const float4*)(p.k_norm_g + f);
	global_load_dwordx2 v[74:75], v[64:65], off
	global_load_dwordx2 v[80:81], v[64:65], off offset:16
	global_load_dwordx2 v[82:83], v[64:65], off offset:32
	global_load_dwordx2 v[96:97], v[64:65], off offset:48
	v_and_b32_e32 v65, 64, v214
	v_xor_b32_e32 v64, 32, v214
	v_add_u32_e32 v65, 64, v65
	v_cmp_lt_i32_e32 vcc, v64, v65
	global_load_dwordx4 v[84:87], v[194:195], off offset:320
	global_load_dwordx4 v[88:91], v[194:195], off offset:352
	global_load_dwordx4 v[76:79], v[194:195], off offset:256
	global_load_dwordx4 v[92:95], v[194:195], off offset:288
	v_add_u32_e32 v238, s42, v184
	v_ashrrev_i32_e32 v238, 3, v238
	v_and_or_b32 v238, v238, s85, v186
	v_lshlrev_b32_e32 v238, 1, v238
	v_ashrrev_i32_e32 v239, 31, v238
	v_lshl_add_u64 v[238:239], v[238:239], 2, s[38:39]
	global_load_dwordx4 v[222:225], v[192:193], off
	global_load_dwordx4 v[226:229], v[192:193], off offset:16
	global_load_dwordx4 v[230:233], v[238:239], off
	global_load_dwordx4 v[234:237], v[238:239], off offset:16
	global_load_dwordx4 v[146:149], v[194:195], off
	global_load_dwordx4 v[150:153], v[194:195], off offset:32
	global_load_dwordx4 v[154:157], v[194:195], off offset:64
	global_load_dwordx4 v[158:161], v[194:195], off offset:96
	global_load_dwordx4 v[162:165], v[194:195], off offset:128
	global_load_dwordx4 v[166:169], v[194:195], off offset:160
	global_load_dwordx4 v[170:173], v[194:195], off offset:192
	global_load_dwordx4 v[174:177], v[194:195], off offset:224
	v_cndmask_b32_e32 v64, v214, v64, vcc
	v_lshlrev_b32_e32 v73, 2, v64
	ds_bpermute_b32 v64, v73, v66
	s_waitcnt lgkmcnt(0)
	v_add_f32_e32 v64, v66, v64
	v_fmamk_f32 v64, v64, 0x3b800000, v206
	v_mul_f32_e32 v65, 0x4b800000, v64
	v_cmp_gt_f32_e32 vcc, s84, v64
	s_waitcnt vmcnt(0)
	v_lshlrev_b32_e32 v122, 16, v74
	v_cndmask_b32_e32 v64, v64, v65, vcc
	v_rsq_f32_e32 v64, v64
	v_and_b32_e32 v123, 0xffff0000, v74
	v_pk_mul_f32 v[142:143], v[122:123], v[122:123]
	v_lshlrev_b32_e32 v74, 16, v75
	v_mul_f32_e32 v65, 0x45800000, v64
	v_cndmask_b32_e32 v72, v64, v65, vcc
	v_pk_mul_f32 v[48:49], v[48:49], v[72:73] op_sel_hi:[1,0]
	v_pk_mul_f32 v[50:51], v[50:51], v[72:73] op_sel_hi:[1,0]
	v_pk_mul_f32 v[70:71], v[38:39], v[72:73] op_sel_hi:[1,0]
	v_pk_mul_f32 v[38:39], v[40:41], v[72:73] op_sel_hi:[1,0]
	v_pk_mul_f32 v[40:41], v[48:49], v[48:49]
	v_pk_mul_f32 v[68:69], v[36:37], v[72:73] op_sel_hi:[1,0]
	v_pk_mul_f32 v[36:37], v[42:43], v[72:73] op_sel_hi:[1,0]
	v_pk_mul_f32 v[42:43], v[50:51], v[50:51]
	v_add_f32_e32 v40, v40, v41
	v_pk_mul_f32 v[52:53], v[52:53], v[72:73] op_sel_hi:[1,0]
	v_add_f32_e32 v40, v42, v40
	v_pk_mul_f32 v[66:67], v[34:35], v[72:73] op_sel_hi:[1,0]
	v_pk_mul_f32 v[34:35], v[44:45], v[72:73] op_sel_hi:[1,0]
	v_pk_mul_f32 v[44:45], v[52:53], v[52:53]
	v_add_f32_e32 v40, v43, v40
	v_pk_mul_f32 v[54:55], v[54:55], v[72:73] op_sel_hi:[1,0]
	v_add_f32_e32 v40, v44, v40
	v_pk_mul_f32 v[64:65], v[32:33], v[72:73] op_sel_hi:[1,0]
	v_pk_mul_f32 v[32:33], v[46:47], v[72:73] op_sel_hi:[1,0]
	v_pk_mul_f32 v[46:47], v[54:55], v[54:55]
	v_add_f32_e32 v40, v45, v40
	v_pk_mul_f32 v[56:57], v[56:57], v[72:73] op_sel_hi:[1,0]
	v_add_f32_e32 v40, v46, v40
	v_pk_mul_f32 v[98:99], v[56:57], v[56:57]
	v_add_f32_e32 v40, v47, v40
	v_pk_mul_f32 v[58:59], v[58:59], v[72:73] op_sel_hi:[1,0]
	v_add_f32_e32 v40, v98, v40
	v_pk_mul_f32 v[100:101], v[58:59], v[58:59]
	v_add_f32_e32 v40, v99, v40
	v_pk_mul_f32 v[60:61], v[60:61], v[72:73] op_sel_hi:[1,0]
	v_add_f32_e32 v40, v100, v40
	v_pk_mul_f32 v[102:103], v[60:61], v[60:61]
	v_add_f32_e32 v40, v101, v40
	v_pk_mul_f32 v[62:63], v[62:63], v[72:73] op_sel_hi:[1,0]
	v_add_f32_e32 v40, v102, v40
	v_pk_mul_f32 v[104:105], v[62:63], v[62:63]
	v_add_f32_e32 v40, v103, v40
	v_add_f32_e32 v40, v104, v40
	v_pk_mul_f32 v[106:107], v[64:65], v[64:65]
	v_add_f32_e32 v40, v105, v40
	v_add_f32_e32 v40, v106, v40
	v_pk_mul_f32 v[108:109], v[66:67], v[66:67]
	v_add_f32_e32 v40, v107, v40
	v_add_f32_e32 v40, v108, v40
	v_pk_mul_f32 v[110:111], v[68:69], v[68:69]
	v_add_f32_e32 v40, v109, v40
	v_add_f32_e32 v40, v110, v40
	v_pk_mul_f32 v[112:113], v[70:71], v[70:71]
	v_add_f32_e32 v40, v111, v40
	v_add_f32_e32 v40, v112, v40
	v_pk_mul_f32 v[114:115], v[38:39], v[38:39]
	v_add_f32_e32 v40, v113, v40
	v_add_f32_e32 v40, v114, v40
	v_pk_mul_f32 v[116:117], v[36:37], v[36:37]
	v_add_f32_e32 v40, v115, v40
	v_add_f32_e32 v40, v116, v40
	v_pk_mul_f32 v[118:119], v[34:35], v[34:35]
	v_add_f32_e32 v40, v117, v40
	v_add_f32_e32 v40, v118, v40
	v_pk_mul_f32 v[120:121], v[32:33], v[32:33]
	v_add_f32_e32 v40, v119, v40
	v_add_f32_e32 v40, v120, v40
	v_add_f32_e32 v40, v121, v40
	v_and_b32_e32 v75, 0xffff0000, v75
	v_add_f32_e32 v40, v142, v40
	v_pk_mul_f32 v[138:139], v[74:75], v[74:75]
	v_add_f32_e32 v40, v143, v40
	v_lshlrev_b32_e32 v124, 16, v80
	v_and_b32_e32 v125, 0xffff0000, v80
	v_add_f32_e32 v40, v138, v40
	v_pk_mul_f32 v[144:145], v[124:125], v[124:125]
	v_add_f32_e32 v40, v139, v40
	v_lshlrev_b32_e32 v80, 16, v81
	v_and_b32_e32 v81, 0xffff0000, v81
	v_add_f32_e32 v40, v144, v40
	v_pk_mul_f32 v[140:141], v[80:81], v[80:81]
	v_add_f32_e32 v40, v145, v40
	v_lshlrev_b32_e32 v126, 16, v82
	v_and_b32_e32 v127, 0xffff0000, v82
	v_add_f32_e32 v40, v140, v40
	v_pk_mul_f32 v[134:135], v[126:127], v[126:127]
	v_add_f32_e32 v40, v141, v40
	v_lshlrev_b32_e32 v128, 16, v83
	v_and_b32_e32 v129, 0xffff0000, v83
	v_add_f32_e32 v40, v134, v40
	v_pk_mul_f32 v[82:83], v[128:129], v[128:129]
	v_add_f32_e32 v40, v135, v40
	v_lshlrev_b32_e32 v130, 16, v96
	v_and_b32_e32 v131, 0xffff0000, v96
	v_add_f32_e32 v40, v82, v40
	v_pk_mul_f32 v[136:137], v[130:131], v[130:131]
	v_add_f32_e32 v40, v83, v40
	v_lshlrev_b32_e32 v96, 16, v97
	v_and_b32_e32 v97, 0xffff0000, v97
	v_add_f32_e32 v40, v136, v40
	v_pk_mul_f32 v[132:133], v[96:97], v[96:97]
	v_add_f32_e32 v40, v137, v40
	v_add_f32_e32 v40, v132, v40
	v_add_f32_e32 v40, v133, v40
	ds_bpermute_b32 v41, v73, v40
	s_waitcnt lgkmcnt(0)
; DI int crow(int i, int hh) { return (i & 3) + 8 * (i >> 2) + 4 * hh; }
; DI void phase3(const Params& p, char* smem) {
;     ...
;       ss += __shfl_xor(ss, 32);
;       const float rk = rsqrtf(ss * (1.f / QKD) + EPS);
; #pragma unroll
;       for (int i = 0; i < 16; ++i) kp[i] *= rk * p.k_norm_g[64 + crow(i, hh)];
;       if (lat) {
;         const int pos = key;
;         const float* tr = p.ropeTab + ((pos >> 6) * 8 + 4 * hh) * 2;
;         const float* tc = p.ropeTab + ((pos & 63) * 8 + 4 * hh) * 2;
; #pragma unroll
;         for (int i = 0; i < 4; ++i) { rope_pair(kp[i], kp[i + 4], tr + 2 * i); rope_pair(kp[8 + i], kp[12 + i], tc + 2 * i); }
;       }
	v_add_f32_e32 v40, v40, v41
	v_fmamk_f32 v40, v40, 0x3c2aaaab, v206
	v_mul_f32_e32 v41, 0x4b800000, v40
	v_cmp_gt_f32_e32 vcc, s84, v40
	s_nop 1
	v_cndmask_b32_e32 v40, v40, v41, vcc
	v_rsq_f32_e32 v40, v40
	s_nop 0
	v_mul_f32_e32 v41, 0x45800000, v40
	v_cndmask_b32_e32 v82, v40, v41, vcc
	v_pk_mul_f32 v[40:41], v[76:77], v[82:83] op_sel_hi:[1,0]
	s_andn2_b64 vcc, exec, s[14:15]
	v_pk_mul_f32 v[76:77], v[40:41], v[122:123]
	v_pk_mul_f32 v[40:41], v[78:79], v[82:83] op_sel_hi:[1,0]
	s_nop 0
	v_pk_mul_f32 v[78:79], v[40:41], v[74:75]
	v_pk_mul_f32 v[40:41], v[92:93], v[82:83] op_sel_hi:[1,0]
	s_nop 0
	v_pk_mul_f32 v[42:43], v[40:41], v[124:125]
	v_pk_mul_f32 v[40:41], v[94:95], v[82:83] op_sel_hi:[1,0]
	s_nop 0
	v_pk_mul_f32 v[46:47], v[40:41], v[80:81]
	v_pk_mul_f32 v[40:41], v[84:85], v[82:83] op_sel_hi:[1,0]
	v_pk_mul_f32 v[80:81], v[90:91], v[82:83] op_sel_hi:[1,0]
	v_pk_mul_f32 v[44:45], v[40:41], v[126:127]
	v_pk_mul_f32 v[40:41], v[86:87], v[82:83] op_sel_hi:[1,0]
	v_pk_mul_f32 v[80:81], v[80:81], v[96:97]
	v_pk_mul_f32 v[74:75], v[40:41], v[128:129]
	v_pk_mul_f32 v[40:41], v[88:89], v[82:83] op_sel_hi:[1,0]
	s_nop 0
	v_pk_mul_f32 v[40:41], v[40:41], v[130:131]
	s_cbranch_vccnz .LBB0_314
	v_add_u32_e32 v73, s42, v184
	v_ashrrev_i32_e32 v73, 3, v73
	v_and_or_b32 v73, v73, s85, v186
	v_lshlrev_b32_e32 v92, 1, v73
	v_ashrrev_i32_e32 v93, 31, v92
	v_mov_b32_e32 v84, v222
	v_mov_b32_e32 v85, v223
	v_mov_b32_e32 v86, v224
	v_mov_b32_e32 v87, v225
	v_mov_b32_e32 v88, v226
	v_mov_b32_e32 v89, v227
	v_mov_b32_e32 v90, v228
	v_mov_b32_e32 v91, v229
	v_lshl_add_u64 v[96:97], v[92:93], 2, s[38:39]
	v_mov_b32_e32 v92, v230
	v_mov_b32_e32 v93, v231
	v_mov_b32_e32 v94, v232
	v_mov_b32_e32 v95, v233
	s_nop 0
	v_mov_b32_e32 v96, v234
	v_mov_b32_e32 v97, v235
	v_mov_b32_e32 v98, v236
	v_mov_b32_e32 v99, v237
	s_waitcnt vmcnt(3)
	v_mov_b32_e32 v101, v86
	v_mov_b32_e32 v86, v85
	v_mov_b32_e32 v100, v84
	s_waitcnt vmcnt(2)
	v_mov_b32_e32 v84, v88
	v_mov_b32_e32 v85, v90
	v_mov_b32_e32 v90, v89
	v_pk_mul_f32 v[88:89], v[44:45], v[86:87]
	v_pk_mul_f32 v[86:87], v[40:41], v[86:87]
	v_pk_mul_f32 v[102:103], v[74:75], v[90:91]
	v_pk_mul_f32 v[90:91], v[80:81], v[90:91]
	v_pk_fma_f32 v[44:45], v[44:45], v[100:101], v[86:87] neg_lo:[0,0,1] neg_hi:[0,0,1]
	v_pk_fma_f32 v[40:41], v[40:41], v[100:101], v[88:89]
	s_waitcnt vmcnt(1)
	v_mov_b32_e32 v87, v94
	v_mov_b32_e32 v94, v93
	s_waitcnt vmcnt(0)
	v_mov_b32_e32 v89, v98
	v_mov_b32_e32 v98, v97
	v_pk_fma_f32 v[74:75], v[74:75], v[84:85], v[90:91] neg_lo:[0,0,1] neg_hi:[0,0,1]
	v_mov_b32_e32 v86, v92
	v_mov_b32_e32 v88, v96
	v_pk_mul_f32 v[90:91], v[76:77], v[94:95]
	v_pk_mul_f32 v[92:93], v[42:43], v[94:95]
	v_pk_mul_f32 v[94:95], v[78:79], v[98:99]
	v_pk_mul_f32 v[96:97], v[46:47], v[98:99]
	v_pk_fma_f32 v[76:77], v[76:77], v[86:87], v[92:93] neg_lo:[0,0,1] neg_hi:[0,0,1]
	v_pk_fma_f32 v[42:43], v[42:43], v[86:87], v[90:91]
	v_pk_fma_f32 v[78:79], v[78:79], v[88:89], v[96:97] neg_lo:[0,0,1] neg_hi:[0,0,1]
	v_pk_fma_f32 v[46:47], v[46:47], v[88:89], v[94:95]
	v_pk_fma_f32 v[80:81], v[80:81], v[84:85], v[102:103]
	s_branch .LBB0_314
